# layer-0 M2 queue: weight-conversion units interleaved 3:1 with the compute units (HBM traffic overlaps attention compute)
# speedup vs baseline: 1.0018x; 1.0013x over previous
; #define LAS __attribute__((address_space(3)))
; __device__ __forceinline__ unsigned pk2(float lo, float hi) { return pg8::cvt_pk_bf16(lo, hi); }
; template <class T> __device__ __forceinline__ LAS T* opq(LAS T* p) { asm volatile("" : "+v"(p)); return p; }
; #define CT_LOAD(R, kbase) do { _Pragma("unroll") for (int _it = 0; _it < 4; ++_it) { R[_it][0] = (f32x4){0.f, 0.f, 0.f, 0.f}; R[_it][1] = (f32x4){0.f, 0.f, 0.f, 0.f}; \
;         if (sc >= 0) { const float* _p = src + (size_t)((kbase) + kk + 64 * _it) * src_ld + sc; R[_it][0] = *(const f32x4*)_p; R[_it][1] = *(const f32x4*)(_p + 4); } } } while (0)
; template <bool MAP, int NT>
; __device__ __forceinline__ void convert_tiles(const Ctx& c, const float* src, int src_ld, bf16* dst, int n0, int k0) {
;     LAS unsigned* tile = opq((LAS unsigned*)c.lds);
;     const int c8 = (c.tid & 7) * 8, kk = c.tid >> 3;
;     const int sc = MAP ? map_in(n0 + c8) : n0 + c8;
;     const int nn = c.tid >> 3, ks = c.tid & 7;
;     f32x4 ra[4][2], rb[4][2];
;     ...
;     CT_LOAD(ra, k0);
; #pragma unroll
;     for (int t = 0; t < NT; ++t) {
;         if (t + 1 < NT) CT_LOAD(rb, k0 + (t + 1) * 256);
;         if (t) __syncthreads();
; #pragma unroll
;         for (int it = 0; it < 4; ++it) {
;             LAS unsigned* tp = tile + (kk + 64 * it) * 37 + (c8 >> 1);
;             tp[0] = pk2(ra[it][0][0], ra[it][0][1]); tp[1] = pk2(ra[it][0][2], ra[it][0][3]); tp[2] = pk2(ra[it][1][0], ra[it][1][1]); tp[3] = pk2(ra[it][1][2], ra[it][1][3]);
;         }
; __device__ __forceinline__ void phase_M2(Ctx& c, int l, int q, const XcdBarrier& bar) {
;     ...
;     for (;;) {
;         const int u = next_unit(c, q);
;         const int pskip = ((int)gridDim.x == 256) ? PRO_NMOD : 0;
;         if (u >= M2_TOTAL + (l == 0 ? PRO_N - pskip : 0)) break;
;         if (u < M2_TOTAL) m2_dispatch(c, l, u); else prologue_unit(c, 1, pskip + u - M2_TOTAL);
.LBB0_1361:
	s_or_b64 exec, exec, s[0:1]
	s_waitcnt lgkmcnt(0)
	s_barrier
	s_load_dword s0, s[12:13], 0x0
	ds_read_b32 v0, v176
	s_waitcnt lgkmcnt(0)
	s_cmpk_eq_i32 s0, 0x100
	s_cselect_b32 s8, 0x60, 0
	v_readfirstlane_b32 s87, v0
	s_cmpk_gt_i32 s87, 0x64f
	s_cbranch_scc1 .Lil_done
	s_cmpk_gt_i32 s87, 0x63f
	s_cbranch_scc1 .Lil_hi
	s_and_b32 s58, s87, 3
	s_cmp_eq_u32 s58, 0
	s_cbranch_scc1 .Lil_m2
	s_add_i32 s58, s87, 3
	s_lshr_b32 s58, s58, 2
	s_sub_i32 s87, s87, s58
	s_addk_i32 s87, 0x1a0
	s_branch .Lil_done
.Lil_m2:
	s_lshr_b32 s87, s87, 2
	s_branch .Lil_done
.Lil_hi:
	s_add_i32 s87, s87, 0xfffffb50
.Lil_done:
	s_sub_i32 s0, 0x6b0, s8
	s_cmp_ge_i32 s87, s0
	s_mov_b64 s[0:1], -1
	s_cbranch_scc1 .LBB0_1356
	s_cmpk_gt_i32 s87, 0x19f
	s_cbranch_scc0 .LBB0_1434
	s_add_i32 s8, s8, s87
	s_add_i32 s2, s8, 0xfffffe60
	s_cmpk_gt_u32 s2, 0x5f
	s_cbranch_scc0 .LBB0_1417
	s_lshl_b32 s0, s2, 10
	s_and_b32 s9, s0, 0xc00
	s_load_dwordx2 s[0:1], s[90:91], 0xc0
	v_lshlrev_b32_e32 v0, 3, v164
	s_lshl_b32 s4, s2, 4
	v_and_b32_e32 v73, 56, v0
	v_ashrrev_i32_e32 v75, 3, v162
	s_cmpk_gt_u32 s2, 0x40f
	s_mov_b64 s[2:3], -1
	v_add_u32_e32 v64, s9, v75
	v_mul_lo_u32 v74, v75, s75
	v_lshlrev_b32_e32 v66, 1, v73
	v_mul_u32_u24_e32 v72, 0x94, v73
	s_cbranch_scc0 .LBB0_1366
	s_load_dwordx2 s[2:3], s[90:91], 0xa8
	s_and_b32 s5, s4, 0x7fffffc0
	s_addk_i32 s5, 0xbf00
	v_or_b32_e32 v160, s5, v73
	v_ashrrev_i32_e32 v65, 31, v64
	s_waitcnt lgkmcnt(0)
	v_lshl_add_u64 v[0:1], v[160:161], 2, s[2:3]
	v_lshlrev_b64 v[2:3], 14, v[64:65]
	v_lshl_add_u64 v[68:69], v[0:1], 0, v[2:3]
	v_add_co_u32_e32 v2, vcc, 0x4000000, v68
	v_mov_b32_e32 v67, v161
	s_mov_b64 s[2:3], 0x4000000
	v_addc_co_u32_e32 v3, vcc, 0, v69, vcc
	v_lshl_add_u64 v[0:1], v[68:69], 0, s[2:3]
	global_load_dwordx4 v[32:35], v[2:3], off
	global_load_dwordx4 v[36:39], v[0:1], off offset:16
	v_add_co_u32_e32 v2, vcc, 0x4100000, v68
	s_mov_b64 s[2:3], 0x4100000
	s_nop 0
	v_addc_co_u32_e32 v3, vcc, 0, v69, vcc
	v_lshl_add_u64 v[0:1], v[68:69], 0, s[2:3]
	global_load_dwordx4 v[40:43], v[2:3], off
	global_load_dwordx4 v[44:47], v[0:1], off offset:16
	v_add_co_u32_e32 v0, vcc, 0x4200000, v68
	s_mov_b64 s[2:3], 0x4200000
	s_nop 0
	v_addc_co_u32_e32 v1, vcc, 0, v69, vcc
	global_load_dwordx4 v[48:51], v[0:1], off
	v_lshl_add_u64 v[0:1], v[68:69], 0, s[2:3]
	global_load_dwordx4 v[52:55], v[0:1], off offset:16
	v_add_co_u32_e32 v0, vcc, 0x4300000, v68
	s_mov_b64 s[2:3], 0x4300000
	s_nop 0
	v_addc_co_u32_e32 v1, vcc, 0, v69, vcc
	global_load_dwordx4 v[56:59], v[0:1], off
	v_lshl_add_u64 v[0:1], v[68:69], 0, s[2:3]
	global_load_dwordx4 v[60:63], v[0:1], off offset:16
	v_add_u32_e32 v0, s5, v75
	v_ashrrev_i32_e32 v1, 31, v0
	v_lshlrev_b64 v[0:1], 13, v[0:1]
	s_mov_b64 s[2:3], 0x4400000
	v_lshl_add_u64 v[70:71], s[0:1], 0, v[0:1]
	v_lshl_add_u64 v[0:1], v[68:69], 0, s[2:3]
	s_mov_b32 s2, 0x4400000
	v_add_co_u32_e32 v2, vcc, s2, v68
	s_mov_b64 s[2:3], 0x4500000
	s_nop 0
	v_addc_co_u32_e32 v3, vcc, 0, v69, vcc
	global_load_dwordx4 v[28:31], v[2:3], off
	global_load_dwordx4 v[12:15], v[0:1], off offset:16
	v_lshl_add_u64 v[0:1], v[68:69], 0, s[2:3]
	s_mov_b32 s2, 0x4500000
	v_add_co_u32_e32 v2, vcc, s2, v68
	s_mov_b64 s[2:3], 0x4600000
	s_nop 0
	v_addc_co_u32_e32 v3, vcc, 0, v69, vcc
	global_load_dwordx4 v[24:27], v[2:3], off
	global_load_dwordx4 v[8:11], v[0:1], off offset:16
	v_lshl_add_u64 v[0:1], v[68:69], 0, s[2:3]
	s_mov_b32 s2, 0x4600000
	v_add_co_u32_e32 v2, vcc, s2, v68
	s_mov_b64 s[2:3], 0x4700000
	s_nop 0
	v_addc_co_u32_e32 v3, vcc, 0, v69, vcc
	global_load_dwordx4 v[20:23], v[2:3], off
	global_load_dwordx4 v[4:7], v[0:1], off offset:16
	v_lshl_add_u64 v[0:1], v[68:69], 0, s[2:3]
	s_mov_b32 s2, 0x4700000
	v_add_co_u32_e32 v2, vcc, s2, v68
	v_add3_u32 v65, v67, v66, v74
	s_nop 0
	v_addc_co_u32_e32 v3, vcc, 0, v69, vcc
	global_load_dwordx4 v[16:19], v[2:3], off
	s_nop 0
	global_load_dwordx4 v[0:3], v[0:1], off offset:16
	v_lshlrev_b32_e32 v76, 1, v75
	s_lshl_b32 s18, s9, 1
	s_mov_b64 s[2:3], 0x11000000
	s_waitcnt vmcnt(15)
	v_cvt_pk_bf16_f32 v32, v32, v33
	ds_write_b32 v65, v32
	v_cvt_pk_bf16_f32 v32, v34, v35
	ds_write_b32 v65, v32 offset:4
	s_waitcnt vmcnt(14)
	v_cvt_pk_bf16_f32 v32, v36, v37
	ds_write_b32 v65, v32 offset:8
	v_cvt_pk_bf16_f32 v32, v38, v39
	ds_write_b32 v65, v32 offset:12
	s_waitcnt vmcnt(13)
	v_cvt_pk_bf16_f32 v32, v40, v41
	ds_write_b32 v65, v32 offset:9472
	v_cvt_pk_bf16_f32 v32, v42, v43
	ds_write_b32 v65, v32 offset:9476
	s_waitcnt vmcnt(12)
	v_cvt_pk_bf16_f32 v32, v44, v45
	ds_write_b32 v65, v32 offset:9480
	v_cvt_pk_bf16_f32 v32, v46, v47
	ds_write_b32 v65, v32 offset:9484
	s_waitcnt vmcnt(11)
	v_cvt_pk_bf16_f32 v32, v48, v49
	ds_write_b32 v65, v32 offset:18944
	v_cvt_pk_bf16_f32 v32, v50, v51
	ds_write_b32 v65, v32 offset:18948
	s_waitcnt vmcnt(10)
	v_cvt_pk_bf16_f32 v32, v52, v53
	ds_write_b32 v65, v32 offset:18952
	v_cvt_pk_bf16_f32 v32, v54, v55
	ds_write_b32 v65, v32 offset:18956
	s_waitcnt vmcnt(9)
	v_cvt_pk_bf16_f32 v32, v56, v57
	ds_write_b32 v65, v32 offset:28416
	v_cvt_pk_bf16_f32 v32, v58, v59
	ds_write_b32 v65, v32 offset:28420
	s_waitcnt vmcnt(8)
	v_cvt_pk_bf16_f32 v32, v60, v61
	ds_write_b32 v65, v32 offset:28424
	v_cvt_pk_bf16_f32 v32, v62, v63
	v_add3_u32 v42, v67, v76, v72
	ds_write_b32 v65, v32 offset:28428
	s_waitcnt lgkmcnt(0)
	s_barrier
; #define LAS __attribute__((address_space(3)))
;     template <class T> __device__ __forceinline__ T* w(size_t off) const { return (T*)(pp->ws + off); }
; template <bool MAP, int NT>
; __device__ __forceinline__ void convert_tiles(const Ctx& c, const float* src, int src_ld, bf16* dst, int n0, int k0) {
;     ...
;         const LAS bf16* th = (const LAS bf16*)tile;
; #pragma unroll
;         for (int it = 0; it < 4; ++it) {
;             const int k8 = ks * 8 + 64 * it;
;             unsigned v[8];
; #pragma unroll
;             for (int i = 0; i < 8; ++i) v[i] = th[(k8 + i) * 74 + nn];
;             u32x4 w; w.x = v[0] | (v[1] << 16); w.y = v[2] | (v[3] << 16); w.z = v[4] | (v[5] << 16); w.w = v[6] | (v[7] << 16);
;             *(u32x4*)(dst + (size_t)(n0 + nn) * 4096 + k0 + t * 256 + k8) = w;
;         }
; #pragma unroll
;         for (int it = 0; it < 4; ++it) { ra[it][0] = rb[it][0]; ra[it][1] = rb[it][1]; }
	ds_read_u16 v32, v42
	ds_read_u16 v33, v42 offset:148
	ds_read_u16 v34, v42 offset:296
	ds_read_u16 v35, v42 offset:444
	ds_read_u16 v38, v42 offset:592
	ds_read_u16 v39, v42 offset:740
	ds_read_u16 v40, v42 offset:888
	ds_read_u16 v41, v42 offset:1036
	v_lshl_add_u64 v[36:37], v[70:71], 0, s[18:19]
	v_mov_b32_e32 v67, v161
	v_lshl_add_u64 v[36:37], v[36:37], 0, v[66:67]
	s_waitcnt lgkmcnt(6)
	v_lshl_or_b32 v32, v33, 16, v32
	s_waitcnt lgkmcnt(4)
	v_lshl_or_b32 v33, v35, 16, v34
	s_waitcnt lgkmcnt(0)
	v_lshl_or_b32 v35, v41, 16, v40
	v_lshl_add_u64 v[40:41], v[36:37], 0, s[2:3]
	s_mov_b32 s2, 0x11000000
	v_lshl_or_b32 v34, v39, 16, v38
	v_add_co_u32_e32 v36, vcc, s2, v36
	ds_read_u16 v38, v42 offset:9472
	ds_read_u16 v39, v42 offset:9620
	ds_read_u16 v43, v42 offset:9768
	ds_read_u16 v44, v42 offset:9916
	ds_read_u16 v45, v42 offset:10064
	ds_read_u16 v46, v42 offset:10212
	ds_read_u16 v47, v42 offset:10360
	ds_read_u16 v48, v42 offset:10508
	v_addc_co_u32_e32 v37, vcc, 0, v37, vcc
	global_store_dwordx4 v[36:37], v[32:35], off
	s_mov_b64 s[2:3], 0x4800000
	v_lshl_add_u64 v[70:71], v[68:69], 0, s[20:21]
	s_waitcnt lgkmcnt(6)
	v_lshl_or_b32 v32, v39, 16, v38
	s_waitcnt lgkmcnt(4)
	v_lshl_or_b32 v33, v44, 16, v43
	s_waitcnt lgkmcnt(2)
	v_lshl_or_b32 v34, v46, 16, v45
	ds_read_u16 v36, v42 offset:18944
	ds_read_u16 v37, v42 offset:19092
	ds_read_u16 v38, v42 offset:19240
	ds_read_u16 v39, v42 offset:19388
	ds_read_u16 v43, v42 offset:19536
	ds_read_u16 v44, v42 offset:19684
	ds_read_u16 v45, v42 offset:19832
	ds_read_u16 v46, v42 offset:19980
	s_waitcnt lgkmcnt(8)
	v_lshl_or_b32 v35, v48, 16, v47
	global_store_dwordx4 v[40:41], v[32:35], off offset:128
	s_waitcnt lgkmcnt(6)
	s_nop 0
	v_lshl_or_b32 v32, v37, 16, v36
	s_waitcnt lgkmcnt(4)
	v_lshl_or_b32 v33, v39, 16, v38
	s_waitcnt lgkmcnt(2)
	v_lshl_or_b32 v34, v44, 16, v43
	s_waitcnt lgkmcnt(0)
	v_lshl_or_b32 v35, v46, 16, v45
	ds_read_u16 v36, v42 offset:28416
	ds_read_u16 v37, v42 offset:28564
	ds_read_u16 v38, v42 offset:28712
	ds_read_u16 v39, v42 offset:28860
	ds_read_u16 v43, v42 offset:29008
	ds_read_u16 v44, v42 offset:29156
	ds_read_u16 v45, v42 offset:29304
	ds_read_u16 v46, v42 offset:29452
	global_store_dwordx4 v[40:41], v[32:35], off offset:256
	s_waitcnt lgkmcnt(6)
	s_nop 0
	v_lshl_or_b32 v32, v37, 16, v36
	s_waitcnt lgkmcnt(4)
	v_lshl_or_b32 v33, v39, 16, v38
	s_waitcnt lgkmcnt(2)
	v_lshl_or_b32 v34, v44, 16, v43
	s_waitcnt lgkmcnt(0)
	v_lshl_or_b32 v35, v46, 16, v45
	v_lshl_add_u64 v[36:37], v[68:69], 0, s[2:3]
	s_mov_b32 s2, 0x4800000
	global_store_dwordx4 v[40:41], v[32:35], off offset:384
	s_nop 1
	v_add_co_u32_e32 v32, vcc, s2, v68
	s_mov_b64 s[2:3], 0x4900000
	s_nop 0
	v_addc_co_u32_e32 v33, vcc, 0, v69, vcc
	v_lshl_add_u64 v[48:49], v[68:69], 0, s[2:3]
	s_mov_b32 s2, 0x4900000
	v_add_co_u32_e32 v44, vcc, s2, v68
	s_mov_b64 s[2:3], 0x4a00000
	s_nop 0
	v_addc_co_u32_e32 v45, vcc, 0, v69, vcc
	v_lshl_add_u64 v[56:57], v[68:69], 0, s[2:3]
	s_mov_b32 s2, 0x4a00000
	v_add_co_u32_e32 v52, vcc, s2, v68
	s_mov_b32 s2, 0x4b00000
	s_nop 0
	v_addc_co_u32_e32 v53, vcc, 0, v69, vcc
	global_load_dwordx4 v[32:35], v[32:33], off
	s_nop 0
	global_load_dwordx4 v[36:39], v[36:37], off offset:16
	v_add_co_u32_e32 v60, vcc, s2, v68
	global_load_dwordx4 v[44:47], v[44:45], off
	s_nop 0
	global_load_dwordx4 v[48:51], v[48:49], off offset:16
	v_addc_co_u32_e32 v61, vcc, 0, v69, vcc
	global_load_dwordx4 v[52:55], v[52:53], off
	s_nop 0
	global_load_dwordx4 v[56:59], v[56:57], off offset:16
	s_nop 0
	global_load_dwordx4 v[60:63], v[60:61], off
	s_nop 0
	global_load_dwordx4 v[76:79], v[70:71], off offset:16
	s_barrier
	s_waitcnt vmcnt(19)
	v_cvt_pk_bf16_f32 v28, v28, v29
	ds_write_b32 v65, v28
	v_cvt_pk_bf16_f32 v28, v30, v31
	ds_write_b32 v65, v28 offset:4
	s_waitcnt vmcnt(18)
	v_cvt_pk_bf16_f32 v12, v12, v13
	ds_write_b32 v65, v12 offset:8
	v_cvt_pk_bf16_f32 v12, v14, v15
	ds_write_b32 v65, v12 offset:12
	s_waitcnt vmcnt(17)
	v_cvt_pk_bf16_f32 v12, v24, v25
	ds_write_b32 v65, v12 offset:9472
	v_cvt_pk_bf16_f32 v12, v26, v27
	ds_write_b32 v65, v12 offset:9476
	s_waitcnt vmcnt(16)
	v_cvt_pk_bf16_f32 v8, v8, v9
	ds_write_b32 v65, v8 offset:9480
	v_cvt_pk_bf16_f32 v8, v10, v11
	ds_write_b32 v65, v8 offset:9484
	s_waitcnt vmcnt(15)
	v_cvt_pk_bf16_f32 v8, v20, v21
	ds_write_b32 v65, v8 offset:18944
	v_cvt_pk_bf16_f32 v8, v22, v23
	ds_write_b32 v65, v8 offset:18948
	s_waitcnt vmcnt(14)
	v_cvt_pk_bf16_f32 v4, v4, v5
	ds_write_b32 v65, v4 offset:18952
	v_cvt_pk_bf16_f32 v4, v6, v7
	ds_write_b32 v65, v4 offset:18956
	s_waitcnt vmcnt(13)
	v_cvt_pk_bf16_f32 v4, v16, v17
	ds_write_b32 v65, v4 offset:28416
	v_cvt_pk_bf16_f32 v4, v18, v19
	ds_write_b32 v65, v4 offset:28420
	s_waitcnt vmcnt(12)
	v_cvt_pk_bf16_f32 v0, v0, v1
	ds_write_b32 v65, v0 offset:28424
	v_cvt_pk_bf16_f32 v0, v2, v3
	ds_write_b32 v65, v0 offset:28428
	s_waitcnt lgkmcnt(0)
	s_barrier
; #define LAS __attribute__((address_space(3)))
;     template <class T> __device__ __forceinline__ T* w(size_t off) const { return (T*)(pp->ws + off); }
; template <bool MAP, int NT>
; __device__ __forceinline__ void convert_tiles(const Ctx& c, const float* src, int src_ld, bf16* dst, int n0, int k0) {
;     ...
;         const LAS bf16* th = (const LAS bf16*)tile;
; #pragma unroll
;         for (int it = 0; it < 4; ++it) {
;             const int k8 = ks * 8 + 64 * it;
;             unsigned v[8];
; #pragma unroll
;             for (int i = 0; i < 8; ++i) v[i] = th[(k8 + i) * 74 + nn];
;             u32x4 w; w.x = v[0] | (v[1] << 16); w.y = v[2] | (v[3] << 16); w.z = v[4] | (v[5] << 16); w.w = v[6] | (v[7] << 16);
;             *(u32x4*)(dst + (size_t)(n0 + nn) * 4096 + k0 + t * 256 + k8) = w;
;         }
; #pragma unroll
;         for (int it = 0; it < 4; ++it) { ra[it][0] = rb[it][0]; ra[it][1] = rb[it][1]; }
	ds_read_u16 v0, v42
	ds_read_u16 v1, v42 offset:148
	ds_read_u16 v2, v42 offset:296
	ds_read_u16 v3, v42 offset:444
	ds_read_u16 v4, v42 offset:592
	ds_read_u16 v5, v42 offset:740
	ds_read_u16 v6, v42 offset:888
	ds_read_u16 v7, v42 offset:1036
	s_waitcnt lgkmcnt(6)
	v_lshl_or_b32 v0, v1, 16, v0
	s_waitcnt lgkmcnt(4)
	v_lshl_or_b32 v1, v3, 16, v2
	s_waitcnt lgkmcnt(2)
	v_lshl_or_b32 v2, v5, 16, v4
	s_mov_b32 s2, 0x4c00000
	s_waitcnt lgkmcnt(0)
	v_lshl_or_b32 v3, v7, 16, v6
	ds_read_u16 v4, v42 offset:9472
	ds_read_u16 v5, v42 offset:9620
	ds_read_u16 v6, v42 offset:9768
	ds_read_u16 v7, v42 offset:9916
	ds_read_u16 v8, v42 offset:10064
	ds_read_u16 v9, v42 offset:10212
	ds_read_u16 v10, v42 offset:10360
	ds_read_u16 v11, v42 offset:10508
	global_store_dwordx4 v[40:41], v[0:3], off offset:512
	v_lshl_add_u64 v[12:13], v[68:69], 0, s[24:25]
	v_lshl_add_u64 v[20:21], v[68:69], 0, s[26:27]
	s_waitcnt lgkmcnt(6)
	v_lshl_or_b32 v0, v5, 16, v4
	s_waitcnt lgkmcnt(4)
	v_lshl_or_b32 v1, v7, 16, v6
	s_waitcnt lgkmcnt(2)
	v_lshl_or_b32 v2, v9, 16, v8
	s_waitcnt lgkmcnt(0)
	v_lshl_or_b32 v3, v11, 16, v10
	ds_read_u16 v4, v42 offset:18944
	ds_read_u16 v5, v42 offset:19092
	ds_read_u16 v6, v42 offset:19240
	ds_read_u16 v7, v42 offset:19388
	ds_read_u16 v8, v42 offset:19536
	ds_read_u16 v9, v42 offset:19684
	ds_read_u16 v10, v42 offset:19832
	ds_read_u16 v11, v42 offset:19980
	global_store_dwordx4 v[40:41], v[0:3], off offset:640
	v_lshl_add_u64 v[28:29], v[68:69], 0, s[28:29]
	s_waitcnt lgkmcnt(6)
	v_lshl_or_b32 v0, v5, 16, v4
	s_waitcnt lgkmcnt(4)
	v_lshl_or_b32 v1, v7, 16, v6
	s_waitcnt lgkmcnt(2)
	v_lshl_or_b32 v2, v9, 16, v8
	s_waitcnt lgkmcnt(0)
	v_lshl_or_b32 v3, v11, 16, v10
	ds_read_u16 v4, v42 offset:28416
	ds_read_u16 v5, v42 offset:28564
	ds_read_u16 v6, v42 offset:28712
	ds_read_u16 v7, v42 offset:28860
	ds_read_u16 v8, v42 offset:29008
	ds_read_u16 v9, v42 offset:29156
	ds_read_u16 v10, v42 offset:29304
	ds_read_u16 v11, v42 offset:29452
	global_store_dwordx4 v[40:41], v[0:3], off offset:768
	s_waitcnt lgkmcnt(6)
	s_nop 0
	v_lshl_or_b32 v0, v5, 16, v4
	s_waitcnt lgkmcnt(4)
	v_lshl_or_b32 v1, v7, 16, v6
	s_waitcnt lgkmcnt(2)
	v_lshl_or_b32 v2, v9, 16, v8
	s_waitcnt lgkmcnt(0)
	v_lshl_or_b32 v3, v11, 16, v10
	global_store_dwordx4 v[40:41], v[0:3], off offset:896
	v_lshl_add_u64 v[4:5], v[68:69], 0, s[22:23]
	s_nop 0
	v_add_co_u32_e32 v0, vcc, s2, v68
	s_mov_b32 s2, 0x4d00000
	s_nop 0
	v_addc_co_u32_e32 v1, vcc, 0, v69, vcc
	global_load_dwordx4 v[0:3], v[0:1], off
	s_nop 0
	global_load_dwordx4 v[4:7], v[4:5], off offset:16
	v_add_co_u32_e32 v8, vcc, s2, v68
	s_mov_b32 s2, 0x4e00000
	s_nop 0
	v_addc_co_u32_e32 v9, vcc, 0, v69, vcc
	global_load_dwordx4 v[8:11], v[8:9], off
	s_nop 0
	global_load_dwordx4 v[12:15], v[12:13], off offset:16
	v_add_co_u32_e32 v16, vcc, s2, v68
	s_mov_b32 s2, 0x4f00000
	s_nop 0
	v_addc_co_u32_e32 v17, vcc, 0, v69, vcc
	global_load_dwordx4 v[16:19], v[16:17], off
	s_nop 0
	global_load_dwordx4 v[20:23], v[20:21], off offset:16
	v_add_co_u32_e32 v24, vcc, s2, v68
	s_mov_b64 s[2:3], 0
	s_nop 0
	v_addc_co_u32_e32 v25, vcc, 0, v69, vcc
	global_load_dwordx4 v[24:27], v[24:25], off
	s_nop 0
	global_load_dwordx4 v[28:31], v[28:29], off offset:16
	s_barrier
	s_waitcnt vmcnt(19)
	v_cvt_pk_bf16_f32 v32, v32, v33
	ds_write_b32 v65, v32
	v_cvt_pk_bf16_f32 v32, v34, v35
	ds_write_b32 v65, v32 offset:4
	s_waitcnt vmcnt(18)
	v_cvt_pk_bf16_f32 v32, v36, v37
	ds_write_b32 v65, v32 offset:8
	v_cvt_pk_bf16_f32 v32, v38, v39
	ds_write_b32 v65, v32 offset:12
	s_waitcnt vmcnt(17)
	v_cvt_pk_bf16_f32 v32, v44, v45
	ds_write_b32 v65, v32 offset:9472
	v_cvt_pk_bf16_f32 v32, v46, v47
	ds_write_b32 v65, v32 offset:9476
	s_waitcnt vmcnt(16)
	v_cvt_pk_bf16_f32 v32, v48, v49
	ds_write_b32 v65, v32 offset:9480
	v_cvt_pk_bf16_f32 v32, v50, v51
	ds_write_b32 v65, v32 offset:9484
	s_waitcnt vmcnt(15)
	v_cvt_pk_bf16_f32 v32, v52, v53
	ds_write_b32 v65, v32 offset:18944
	v_cvt_pk_bf16_f32 v32, v54, v55
	ds_write_b32 v65, v32 offset:18948
	s_waitcnt vmcnt(14)
	v_cvt_pk_bf16_f32 v32, v56, v57
	ds_write_b32 v65, v32 offset:18952
	v_cvt_pk_bf16_f32 v32, v58, v59
	ds_write_b32 v65, v32 offset:18956
	s_waitcnt vmcnt(13)
	v_cvt_pk_bf16_f32 v32, v60, v61
	ds_write_b32 v65, v32 offset:28416
	v_cvt_pk_bf16_f32 v32, v62, v63
	ds_write_b32 v65, v32 offset:28420
	s_waitcnt vmcnt(12)
	v_cvt_pk_bf16_f32 v32, v76, v77
	ds_write_b32 v65, v32 offset:28424
	v_cvt_pk_bf16_f32 v32, v78, v79
	ds_write_b32 v65, v32 offset:28428
	s_waitcnt lgkmcnt(0)
	s_barrier
; #define LAS __attribute__((address_space(3)))
;     template <class T> __device__ __forceinline__ T* w(size_t off) const { return (T*)(pp->ws + off); }
; template <bool MAP, int NT>
; __device__ __forceinline__ void convert_tiles(const Ctx& c, const float* src, int src_ld, bf16* dst, int n0, int k0) {
;     ...
;         const LAS bf16* th = (const LAS bf16*)tile;
; #pragma unroll
;         for (int it = 0; it < 4; ++it) {
;             const int k8 = ks * 8 + 64 * it;
;             unsigned v[8];
; #pragma unroll
;             for (int i = 0; i < 8; ++i) v[i] = th[(k8 + i) * 74 + nn];
;             u32x4 w; w.x = v[0] | (v[1] << 16); w.y = v[2] | (v[3] << 16); w.z = v[4] | (v[5] << 16); w.w = v[6] | (v[7] << 16);
;             *(u32x4*)(dst + (size_t)(n0 + nn) * 4096 + k0 + t * 256 + k8) = w;
;         }
; #pragma unroll
;         for (int it = 0; it < 4; ++it) { ra[it][0] = rb[it][0]; ra[it][1] = rb[it][1]; }
	ds_read_u16 v32, v42
	ds_read_u16 v33, v42 offset:148
	ds_read_u16 v34, v42 offset:296
	ds_read_u16 v35, v42 offset:444
	ds_read_u16 v36, v42 offset:592
	ds_read_u16 v37, v42 offset:740
	ds_read_u16 v38, v42 offset:888
	ds_read_u16 v39, v42 offset:1036
	s_waitcnt lgkmcnt(6)
	v_lshl_or_b32 v32, v33, 16, v32
	s_waitcnt lgkmcnt(4)
	v_lshl_or_b32 v33, v35, 16, v34
	s_waitcnt lgkmcnt(2)
	v_lshl_or_b32 v34, v37, 16, v36
	s_waitcnt lgkmcnt(0)
	v_lshl_or_b32 v35, v39, 16, v38
	ds_read_u16 v36, v42 offset:9472
	ds_read_u16 v37, v42 offset:9620
	ds_read_u16 v38, v42 offset:9768
	ds_read_u16 v39, v42 offset:9916
	ds_read_u16 v43, v42 offset:10064
	ds_read_u16 v44, v42 offset:10212
	ds_read_u16 v45, v42 offset:10360
	ds_read_u16 v46, v42 offset:10508
	global_store_dwordx4 v[40:41], v[32:35], off offset:1024
	s_waitcnt lgkmcnt(6)
	s_nop 0
	v_lshl_or_b32 v32, v37, 16, v36
	s_waitcnt lgkmcnt(4)
	v_lshl_or_b32 v33, v39, 16, v38
	s_waitcnt lgkmcnt(2)
	v_lshl_or_b32 v34, v44, 16, v43
	s_waitcnt lgkmcnt(0)
	v_lshl_or_b32 v35, v46, 16, v45
	ds_read_u16 v36, v42 offset:18944
	ds_read_u16 v37, v42 offset:19092
	ds_read_u16 v38, v42 offset:19240
	ds_read_u16 v39, v42 offset:19388
	ds_read_u16 v43, v42 offset:19536
	ds_read_u16 v44, v42 offset:19684
	ds_read_u16 v45, v42 offset:19832
	ds_read_u16 v46, v42 offset:19980
	global_store_dwordx4 v[40:41], v[32:35], off offset:1152
	s_waitcnt lgkmcnt(6)
	s_nop 0
	v_lshl_or_b32 v32, v37, 16, v36
	s_waitcnt lgkmcnt(4)
	v_lshl_or_b32 v33, v39, 16, v38
	s_waitcnt lgkmcnt(2)
	v_lshl_or_b32 v34, v44, 16, v43
	s_waitcnt lgkmcnt(0)
	v_lshl_or_b32 v35, v46, 16, v45
	ds_read_u16 v36, v42 offset:28416
	ds_read_u16 v37, v42 offset:28564
	ds_read_u16 v38, v42 offset:28712
	ds_read_u16 v39, v42 offset:28860
	ds_read_u16 v43, v42 offset:29008
	ds_read_u16 v44, v42 offset:29156
	ds_read_u16 v45, v42 offset:29304
	ds_read_u16 v46, v42 offset:29452
	global_store_dwordx4 v[40:41], v[32:35], off offset:1280
	s_waitcnt lgkmcnt(6)
	s_nop 0
	v_lshl_or_b32 v32, v37, 16, v36
	s_waitcnt lgkmcnt(4)
	v_lshl_or_b32 v33, v39, 16, v38
	s_waitcnt lgkmcnt(2)
	v_lshl_or_b32 v34, v44, 16, v43
	s_waitcnt lgkmcnt(0)
	v_lshl_or_b32 v35, v46, 16, v45
	global_store_dwordx4 v[40:41], v[32:35], off offset:1408
	s_barrier
	s_waitcnt vmcnt(11)
	v_cvt_pk_bf16_f32 v0, v0, v1
	ds_write_b32 v65, v0
	v_cvt_pk_bf16_f32 v0, v2, v3
	ds_write_b32 v65, v0 offset:4
	s_waitcnt vmcnt(10)
	v_cvt_pk_bf16_f32 v0, v4, v5
	ds_write_b32 v65, v0 offset:8
	v_cvt_pk_bf16_f32 v0, v6, v7
	ds_write_b32 v65, v0 offset:12
	s_waitcnt vmcnt(9)
	v_cvt_pk_bf16_f32 v0, v8, v9
	ds_write_b32 v65, v0 offset:9472
	v_cvt_pk_bf16_f32 v0, v10, v11
	ds_write_b32 v65, v0 offset:9476
	s_waitcnt vmcnt(8)
	v_cvt_pk_bf16_f32 v0, v12, v13
	ds_write_b32 v65, v0 offset:9480
	v_cvt_pk_bf16_f32 v0, v14, v15
	ds_write_b32 v65, v0 offset:9484
	s_waitcnt vmcnt(7)
	v_cvt_pk_bf16_f32 v0, v16, v17
	ds_write_b32 v65, v0 offset:18944
	v_cvt_pk_bf16_f32 v0, v18, v19
	ds_write_b32 v65, v0 offset:18948
	s_waitcnt vmcnt(6)
	v_cvt_pk_bf16_f32 v0, v20, v21
	ds_write_b32 v65, v0 offset:18952
	v_cvt_pk_bf16_f32 v0, v22, v23
	ds_write_b32 v65, v0 offset:18956
	s_waitcnt vmcnt(5)
	v_cvt_pk_bf16_f32 v0, v24, v25
	ds_write_b32 v65, v0 offset:28416
	v_cvt_pk_bf16_f32 v0, v26, v27
	ds_write_b32 v65, v0 offset:28420
	s_waitcnt vmcnt(4)
	v_cvt_pk_bf16_f32 v0, v28, v29
	ds_write_b32 v65, v0 offset:28424
	v_cvt_pk_bf16_f32 v0, v30, v31
	ds_write_b32 v65, v0 offset:28428
	s_waitcnt lgkmcnt(0)
	s_barrier
	ds_read_u16 v0, v42
	ds_read_u16 v1, v42 offset:148
	ds_read_u16 v2, v42 offset:296
	ds_read_u16 v3, v42 offset:444
	ds_read_u16 v4, v42 offset:592
	ds_read_u16 v5, v42 offset:740
	ds_read_u16 v6, v42 offset:888
	ds_read_u16 v7, v42 offset:1036
	s_waitcnt lgkmcnt(6)
	v_lshl_or_b32 v0, v1, 16, v0
	s_waitcnt lgkmcnt(4)
	v_lshl_or_b32 v1, v3, 16, v2
	s_waitcnt lgkmcnt(2)
	v_lshl_or_b32 v2, v5, 16, v4
	s_waitcnt lgkmcnt(0)
	v_lshl_or_b32 v3, v7, 16, v6
	ds_read_u16 v4, v42 offset:9472
	ds_read_u16 v5, v42 offset:9620
	ds_read_u16 v6, v42 offset:9768
	ds_read_u16 v7, v42 offset:9916
	ds_read_u16 v8, v42 offset:10064
	ds_read_u16 v9, v42 offset:10212
	ds_read_u16 v10, v42 offset:10360
	ds_read_u16 v11, v42 offset:10508
	global_store_dwordx4 v[40:41], v[0:3], off offset:1536
	s_waitcnt lgkmcnt(6)
	s_nop 0
	v_lshl_or_b32 v0, v5, 16, v4
	s_waitcnt lgkmcnt(4)
	v_lshl_or_b32 v1, v7, 16, v6
	s_waitcnt lgkmcnt(2)
	v_lshl_or_b32 v2, v9, 16, v8
	s_waitcnt lgkmcnt(0)
	v_lshl_or_b32 v3, v11, 16, v10
	ds_read_u16 v4, v42 offset:18944
	ds_read_u16 v5, v42 offset:19092
	ds_read_u16 v6, v42 offset:19240
	ds_read_u16 v7, v42 offset:19388
	ds_read_u16 v8, v42 offset:19536
	ds_read_u16 v9, v42 offset:19684
	ds_read_u16 v10, v42 offset:19832
	ds_read_u16 v11, v42 offset:19980
	global_store_dwordx4 v[40:41], v[0:3], off offset:1664
	s_waitcnt lgkmcnt(6)
	s_nop 0
	v_lshl_or_b32 v0, v5, 16, v4
	s_waitcnt lgkmcnt(4)
	v_lshl_or_b32 v1, v7, 16, v6
	s_waitcnt lgkmcnt(2)
	v_lshl_or_b32 v2, v9, 16, v8
	s_waitcnt lgkmcnt(0)
	v_lshl_or_b32 v3, v11, 16, v10
	ds_read_u16 v4, v42 offset:28416
	ds_read_u16 v5, v42 offset:28564
	ds_read_u16 v6, v42 offset:28712
	ds_read_u16 v7, v42 offset:28860
	ds_read_u16 v8, v42 offset:29008
	ds_read_u16 v9, v42 offset:29156
	ds_read_u16 v10, v42 offset:29304
	ds_read_u16 v11, v42 offset:29452
	global_store_dwordx4 v[40:41], v[0:3], off offset:1792
	s_waitcnt lgkmcnt(6)
	s_nop 0
	v_lshl_or_b32 v0, v5, 16, v4
	s_waitcnt lgkmcnt(4)
	v_lshl_or_b32 v1, v7, 16, v6
	s_waitcnt lgkmcnt(2)
	v_lshl_or_b32 v2, v9, 16, v8
	s_waitcnt lgkmcnt(0)
	v_lshl_or_b32 v3, v11, 16, v10
	global_store_dwordx4 v[40:41], v[0:3], off offset:1920
